# c2 plus: waves 4-7 take the tile-entry stagger barrier before their epilogue stores (W_in and MLP-up GEMMs) so waves 0-3 start the next tile's first MFMA phase while stores still issue; stray vmcnt(0)
# speedup vs baseline: 1.0041x; 1.0010x over previous
; #define PG8_BAR __builtin_amdgcn_s_barrier()
;     ...
;         if (wr == 0) PG8_BAR;
;         E(acc, cur, wr, wc, fr, fq);
;         if (!has_next) break;
; #pragma unroll
;         for (int a = 0; a < 2; ++a)
; #pragma unroll
;             for (int b = 0; b < 2; ++b)
; #pragma unroll
;                 for (int m = 0; m < 4; ++m)
; #pragma unroll
;                     for (int n = 0; n < 2; ++n) acc[a][b][m][n] = (f32x4){0.f, 0.f, 0.f, 0.f};
;         cur = nxt; cA = nA; cB = nB; ++ui;
;         if (wr == 1) PG8_BAR;
.LBB0_120:
	s_and_b64 vcc, s[40:41], s[4:5]
	s_cbranch_vccz .Lse_g1
	s_barrier

; #define PG8_BAR __builtin_amdgcn_s_barrier()
;     ...
;         cur = nxt; cA = nA; cB = nB; ++ui;
;         if (wr == 1) PG8_BAR;
.LBB0_129:
	s_andn2_b64 vcc, exec, s[4:5]
	s_cbranch_vccnz .LBB0_107
	s_branch .LBB0_107

; __device__ __forceinline__ unsigned cvt_pk_bf16(float lo, float hi) { unsigned r; asm volatile("v_cvt_pk_bf16_f32 %0, %1, %2" : "=v"(r) : "v"(lo), "v"(hi)); return r; }
;     __device__ __forceinline__ void operator()(const AccT& acc, const Unit& u, int wr, int wc, int fr, int fq) const {
;     ...
;         float rs[8]; rstd8_cached(rs, ss, (stage << 8) | u.pm, u.pm, rl, wr, wc, fr, fq);
; #pragma unroll
;         for (int ai = 0; ai < 2; ++ai)
; #pragma unroll
;             for (int m = 0; m < 4; ++m) { bf16_t* rowp = U + (size_t)(row0 + ai * 128 + m * 16) * FF + col0;
;                 const float rstd = rs[ai * 4 + m];
; #pragma unroll
;                 for (int bj = 0; bj < 2; ++bj) { f32x4 v0 = acc[ai][bj][m][0], v1 = acc[ai][bj][m][1];
; #pragma unroll
;                     for (int j = 0; j < 4; ++j) { const float a = fmaxf(v0[j], 0.f) * rstd, b = fmaxf(v1[j], 0.f) * rstd; v0[j] = a * a; v1[j] = b * b; }
;                     u32x4 w; w.x = cvt_pk_bf16(v0[0], v0[1]); w.y = cvt_pk_bf16(v0[2], v0[3]); w.z = cvt_pk_bf16(v1[0], v1[1]); w.w = cvt_pk_bf16(v1[2], v1[3]);
;                     *(u32x4*)(rowp + bj * 128) = w; } }
.LBB0_782:
	s_and_b64 vcc, s[44:45], s[6:7]
	s_cbranch_vccz .Lse_g6
	s_barrier
.Lse_g6:
	ds_read2_b32 v[160:161], v157 offset1:16
	ds_read2_b32 v[146:147], v157 offset0:32 offset1:48
	ds_read2_b32 v[144:145], v158 offset1:16
	ds_read2_b32 v[140:141], v158 offset0:32 offset1:48
	v_max_f32_e32 v122, v122, v122
	v_add_u32_e32 v148, s13, v152
	v_max_f32_e32 v122, 0, v122
	v_max_f32_e32 v123, v123, v123
	v_max_f32_e32 v124, v124, v124
	v_ashrrev_i32_e32 v149, 31, v148
	s_waitcnt lgkmcnt(0)
	v_mul_f32_e32 v122, v122, v160
	v_max_f32_e32 v123, 0, v123
	v_max_f32_e32 v124, 0, v124
	v_lshlrev_b64 v[150:151], 14, v[148:149]
	v_mul_f32_e32 v149, v122, v122
	v_max_f32_e32 v122, v127, v127
	v_mul_f32_e32 v123, v123, v160
	v_mul_f32_e32 v124, v124, v160
	v_lshl_or_b32 v142, s36, 8, v154
	v_max_f32_e32 v126, v126, v126
	v_max_f32_e32 v122, 0, v122
	v_mul_f32_e32 v127, v123, v123
	v_max_f32_e32 v123, v128, v128
	v_mul_f32_e32 v128, v124, v124
	v_max_f32_e32 v124, v129, v129
	v_max_f32_e32 v125, v125, v125
	v_ashrrev_i32_e32 v143, 31, v142
	v_max_f32_e32 v126, 0, v126
	v_mul_f32_e32 v122, v122, v160
	v_max_f32_e32 v123, 0, v123
	v_max_f32_e32 v124, 0, v124
	v_max_f32_e32 v125, 0, v125
	v_max_f32_e32 v114, v114, v114
	v_max_f32_e32 v115, v115, v115
	v_max_f32_e32 v116, v116, v116
	v_lshl_add_u64 v[162:163], s[8:9], 0, v[150:151]
	v_lshlrev_b64 v[150:151], 1, v[142:143]
	v_mul_f32_e32 v126, v126, v160
	v_mul_f32_e32 v122, v122, v122
	v_mul_f32_e32 v123, v123, v160
	v_mul_f32_e32 v124, v124, v160
	v_mul_f32_e32 v125, v125, v160
	v_max_f32_e32 v114, 0, v114
	v_max_f32_e32 v115, 0, v115
	v_max_f32_e32 v116, 0, v116
	v_lshl_add_u64 v[142:143], v[162:163], 0, v[150:151]
	v_mul_f32_e32 v126, v126, v126
	v_mul_f32_e32 v123, v123, v123
	v_mul_f32_e32 v124, v124, v124
	v_mul_f32_e32 v125, v125, v125
	v_cvt_pk_bf16_f32 v122, v126, v122
	v_mul_f32_e32 v114, v114, v160
	v_mul_f32_e32 v115, v115, v160
	v_mul_f32_e32 v116, v116, v160
	v_cvt_pk_bf16_f32 v123, v123, v124
	v_cvt_pk_bf16_f32 v124, v149, v127
	v_cvt_pk_bf16_f32 v125, v128, v125
	global_store_dwordx4 v[142:143], v[122:125], off
	v_max_f32_e32 v118, v118, v118
	v_max_f32_e32 v117, v117, v117
	v_mul_f32_e32 v122, v114, v114
	v_max_f32_e32 v114, v119, v119
	v_mul_f32_e32 v119, v115, v115
	v_max_f32_e32 v115, v120, v120
	v_mul_f32_e32 v120, v116, v116
	v_max_f32_e32 v116, v121, v121
	v_max_f32_e32 v114, 0, v114
	v_max_f32_e32 v115, 0, v115
	v_max_f32_e32 v116, 0, v116
	v_max_f32_e32 v118, 0, v118
	v_mul_f32_e32 v114, v114, v160
	v_mul_f32_e32 v115, v115, v160
	v_mul_f32_e32 v116, v116, v160
	v_max_f32_e32 v117, 0, v117
	v_max_f32_e32 v106, v106, v106
	v_mul_f32_e32 v118, v118, v160
	v_mul_f32_e32 v114, v114, v114
	v_mul_f32_e32 v115, v115, v115
	v_mul_f32_e32 v117, v117, v160
	v_mul_f32_e32 v116, v116, v116
	v_max_f32_e32 v106, 0, v106
	v_max_f32_e32 v107, v107, v107
	v_max_f32_e32 v108, v108, v108
	v_mul_f32_e32 v118, v118, v118
	v_mul_f32_e32 v117, v117, v117
	v_cvt_pk_bf16_f32 v114, v118, v114
	v_cvt_pk_bf16_f32 v115, v115, v116
	v_cvt_pk_bf16_f32 v116, v122, v119
	v_mul_f32_e32 v106, v106, v161
	v_max_f32_e32 v107, 0, v107
	v_max_f32_e32 v108, 0, v108
	v_cvt_pk_bf16_f32 v117, v120, v117
	global_store_dwordx4 v[142:143], v[114:117], off offset:256
	v_mul_f32_e32 v107, v107, v161
	v_mul_f32_e32 v108, v108, v161
	v_or_b32_e32 v114, 16, v148
	v_mul_f32_e32 v116, v106, v106
	v_max_f32_e32 v106, v111, v111
	v_ashrrev_i32_e32 v115, 31, v114
	v_max_f32_e32 v110, v110, v110
	v_max_f32_e32 v106, 0, v106
	v_mul_f32_e32 v111, v107, v107
	v_max_f32_e32 v107, v112, v112
	v_mul_f32_e32 v112, v108, v108
	v_max_f32_e32 v108, v113, v113
	v_max_f32_e32 v109, v109, v109
	v_lshlrev_b64 v[114:115], 14, v[114:115]
	v_max_f32_e32 v110, 0, v110
	v_mul_f32_e32 v106, v106, v161
	v_max_f32_e32 v107, 0, v107
	v_max_f32_e32 v108, 0, v108
	v_max_f32_e32 v109, 0, v109
	v_max_f32_e32 v98, v98, v98
	v_max_f32_e32 v99, v99, v99
	v_max_f32_e32 v100, v100, v100
	v_lshl_add_u64 v[114:115], s[8:9], 0, v[114:115]
	v_mul_f32_e32 v110, v110, v161
	v_mul_f32_e32 v106, v106, v106
	v_mul_f32_e32 v107, v107, v161
	v_mul_f32_e32 v108, v108, v161
	v_mul_f32_e32 v109, v109, v161
	v_max_f32_e32 v98, 0, v98
	v_max_f32_e32 v99, 0, v99
	v_max_f32_e32 v100, 0, v100
	v_lshl_add_u64 v[114:115], v[114:115], 0, v[150:151]
	v_mul_f32_e32 v110, v110, v110
	v_mul_f32_e32 v107, v107, v107
	v_mul_f32_e32 v108, v108, v108
	v_mul_f32_e32 v109, v109, v109
	v_cvt_pk_bf16_f32 v106, v110, v106
	v_mul_f32_e32 v98, v98, v161
	v_mul_f32_e32 v99, v99, v161
	v_mul_f32_e32 v100, v100, v161
	v_cvt_pk_bf16_f32 v107, v107, v108
	v_cvt_pk_bf16_f32 v108, v116, v111
	v_cvt_pk_bf16_f32 v109, v112, v109
	global_store_dwordx4 v[114:115], v[106:109], off
	v_max_f32_e32 v102, v102, v102
	v_max_f32_e32 v101, v101, v101
	v_mul_f32_e32 v106, v98, v98
	v_max_f32_e32 v98, v103, v103
	v_mul_f32_e32 v103, v99, v99
	v_max_f32_e32 v99, v104, v104
	v_mul_f32_e32 v104, v100, v100
	v_max_f32_e32 v100, v105, v105
	v_max_f32_e32 v98, 0, v98
	v_max_f32_e32 v99, 0, v99
	v_max_f32_e32 v100, 0, v100
	v_max_f32_e32 v102, 0, v102
	v_mul_f32_e32 v98, v98, v161
	v_mul_f32_e32 v99, v99, v161
	v_mul_f32_e32 v100, v100, v161
	v_max_f32_e32 v101, 0, v101
	v_max_f32_e32 v90, v90, v90
	v_mul_f32_e32 v102, v102, v161
	v_mul_f32_e32 v98, v98, v98
	v_mul_f32_e32 v99, v99, v99
	v_mul_f32_e32 v101, v101, v161
	v_mul_f32_e32 v100, v100, v100
	v_max_f32_e32 v90, 0, v90
	v_max_f32_e32 v91, v91, v91
	v_max_f32_e32 v92, v92, v92
	v_mul_f32_e32 v102, v102, v102
	v_mul_f32_e32 v101, v101, v101
	v_cvt_pk_bf16_f32 v98, v102, v98
	v_cvt_pk_bf16_f32 v99, v99, v100
	v_cvt_pk_bf16_f32 v100, v106, v103
	v_mul_f32_e32 v90, v90, v146
; __device__ __forceinline__ unsigned cvt_pk_bf16(float lo, float hi) { unsigned r; asm volatile("v_cvt_pk_bf16_f32 %0, %1, %2" : "=v"(r) : "v"(lo), "v"(hi)); return r; }
;     __device__ __forceinline__ void operator()(const AccT& acc, const Unit& u, int wr, int wc, int fr, int fq) const {
;     ...
;         for (int ai = 0; ai < 2; ++ai)
; #pragma unroll
;             for (int m = 0; m < 4; ++m) { bf16_t* rowp = U + (size_t)(row0 + ai * 128 + m * 16) * FF + col0;
;                 const float rstd = rs[ai * 4 + m];
; #pragma unroll
;                 for (int bj = 0; bj < 2; ++bj) { f32x4 v0 = acc[ai][bj][m][0], v1 = acc[ai][bj][m][1];
; #pragma unroll
;                     for (int j = 0; j < 4; ++j) { const float a = fmaxf(v0[j], 0.f) * rstd, b = fmaxf(v1[j], 0.f) * rstd; v0[j] = a * a; v1[j] = b * b; }
;                     u32x4 w; w.x = cvt_pk_bf16(v0[0], v0[1]); w.y = cvt_pk_bf16(v0[2], v0[3]); w.z = cvt_pk_bf16(v1[0], v1[1]); w.w = cvt_pk_bf16(v1[2], v1[3]);
;                     *(u32x4*)(rowp + bj * 128) = w; } }
	v_max_f32_e32 v91, 0, v91
	v_max_f32_e32 v92, 0, v92
	v_cvt_pk_bf16_f32 v101, v104, v101
	global_store_dwordx4 v[114:115], v[98:101], off offset:256
	v_mul_f32_e32 v91, v91, v146
	v_mul_f32_e32 v92, v92, v146
	v_or_b32_e32 v98, 32, v148
	v_mul_f32_e32 v100, v90, v90
	v_max_f32_e32 v90, v95, v95
	v_ashrrev_i32_e32 v99, 31, v98
	v_max_f32_e32 v94, v94, v94
	v_max_f32_e32 v90, 0, v90
	v_mul_f32_e32 v95, v91, v91
	v_max_f32_e32 v91, v96, v96
	v_mul_f32_e32 v96, v92, v92
	v_max_f32_e32 v92, v97, v97
	v_max_f32_e32 v93, v93, v93
	v_lshlrev_b64 v[98:99], 14, v[98:99]
	v_max_f32_e32 v94, 0, v94
	v_mul_f32_e32 v90, v90, v146
	v_max_f32_e32 v91, 0, v91
	v_max_f32_e32 v92, 0, v92
	v_max_f32_e32 v93, 0, v93
	v_max_f32_e32 v82, v82, v82
	v_max_f32_e32 v83, v83, v83
	v_max_f32_e32 v84, v84, v84
	v_lshl_add_u64 v[98:99], s[8:9], 0, v[98:99]
	v_mul_f32_e32 v94, v94, v146
	v_mul_f32_e32 v90, v90, v90
	v_mul_f32_e32 v91, v91, v146
	v_mul_f32_e32 v92, v92, v146
	v_mul_f32_e32 v93, v93, v146
	v_max_f32_e32 v82, 0, v82
	v_max_f32_e32 v83, 0, v83
	v_max_f32_e32 v84, 0, v84
	v_lshl_add_u64 v[98:99], v[98:99], 0, v[150:151]
	v_mul_f32_e32 v94, v94, v94
	v_mul_f32_e32 v91, v91, v91
	v_mul_f32_e32 v92, v92, v92
	v_mul_f32_e32 v93, v93, v93
	v_cvt_pk_bf16_f32 v90, v94, v90
	v_mul_f32_e32 v82, v82, v146
	v_mul_f32_e32 v83, v83, v146
	v_mul_f32_e32 v84, v84, v146
	v_cvt_pk_bf16_f32 v91, v91, v92
	v_cvt_pk_bf16_f32 v92, v100, v95
	v_cvt_pk_bf16_f32 v93, v96, v93
	global_store_dwordx4 v[98:99], v[90:93], off
	v_max_f32_e32 v86, v86, v86
	v_max_f32_e32 v85, v85, v85
	v_mul_f32_e32 v90, v82, v82
	v_max_f32_e32 v82, v87, v87
	v_mul_f32_e32 v87, v83, v83
	v_max_f32_e32 v83, v88, v88
	v_mul_f32_e32 v88, v84, v84
	v_max_f32_e32 v84, v89, v89
	v_max_f32_e32 v82, 0, v82
	v_max_f32_e32 v83, 0, v83
	v_max_f32_e32 v84, 0, v84
	v_max_f32_e32 v86, 0, v86
	v_mul_f32_e32 v82, v82, v146
	v_mul_f32_e32 v83, v83, v146
	v_mul_f32_e32 v84, v84, v146
	v_max_f32_e32 v85, 0, v85
	v_max_f32_e32 v74, v74, v74
	v_mul_f32_e32 v86, v86, v146
	v_mul_f32_e32 v82, v82, v82
	v_mul_f32_e32 v83, v83, v83
	v_mul_f32_e32 v85, v85, v146
	v_mul_f32_e32 v84, v84, v84
	v_max_f32_e32 v74, 0, v74
	v_max_f32_e32 v75, v75, v75
	v_max_f32_e32 v76, v76, v76
	v_mul_f32_e32 v86, v86, v86
	v_mul_f32_e32 v85, v85, v85
	v_cvt_pk_bf16_f32 v82, v86, v82
	v_cvt_pk_bf16_f32 v83, v83, v84
	v_cvt_pk_bf16_f32 v84, v90, v87
	v_mul_f32_e32 v74, v74, v147
	v_max_f32_e32 v75, 0, v75
	v_max_f32_e32 v76, 0, v76
	v_cvt_pk_bf16_f32 v85, v88, v85
	global_store_dwordx4 v[98:99], v[82:85], off offset:256
	v_mul_f32_e32 v75, v75, v147
	v_mul_f32_e32 v76, v76, v147
	v_or_b32_e32 v82, 48, v148
	v_mul_f32_e32 v84, v74, v74
	v_max_f32_e32 v74, v79, v79
	v_ashrrev_i32_e32 v83, 31, v82
	v_max_f32_e32 v78, v78, v78
	v_max_f32_e32 v74, 0, v74
	v_mul_f32_e32 v79, v75, v75
	v_max_f32_e32 v75, v80, v80
	v_mul_f32_e32 v80, v76, v76
	v_max_f32_e32 v76, v81, v81
	v_max_f32_e32 v77, v77, v77
	v_lshlrev_b64 v[82:83], 14, v[82:83]
	v_max_f32_e32 v78, 0, v78
	v_mul_f32_e32 v74, v74, v147
	v_max_f32_e32 v75, 0, v75
	v_max_f32_e32 v76, 0, v76
	v_max_f32_e32 v77, 0, v77
	v_max_f32_e32 v66, v66, v66
	v_max_f32_e32 v67, v67, v67
	v_max_f32_e32 v68, v68, v68
	v_lshl_add_u64 v[82:83], s[8:9], 0, v[82:83]
	v_mul_f32_e32 v78, v78, v147
	v_mul_f32_e32 v74, v74, v74
	v_mul_f32_e32 v75, v75, v147
	v_mul_f32_e32 v76, v76, v147
	v_mul_f32_e32 v77, v77, v147
	v_max_f32_e32 v66, 0, v66
	v_max_f32_e32 v67, 0, v67
	v_max_f32_e32 v68, 0, v68
	v_lshl_add_u64 v[82:83], v[82:83], 0, v[150:151]
	v_mul_f32_e32 v78, v78, v78
	v_mul_f32_e32 v75, v75, v75
	v_mul_f32_e32 v76, v76, v76
	v_mul_f32_e32 v77, v77, v77
	v_cvt_pk_bf16_f32 v74, v78, v74
	v_mul_f32_e32 v66, v66, v147
	v_mul_f32_e32 v67, v67, v147
	v_mul_f32_e32 v68, v68, v147
	v_cvt_pk_bf16_f32 v75, v75, v76
	v_cvt_pk_bf16_f32 v76, v84, v79
	v_cvt_pk_bf16_f32 v77, v80, v77
	global_store_dwordx4 v[82:83], v[74:77], off
	v_max_f32_e32 v70, v70, v70
	v_max_f32_e32 v69, v69, v69
	v_mul_f32_e32 v74, v66, v66
	v_max_f32_e32 v66, v71, v71
	v_mul_f32_e32 v71, v67, v67
	v_max_f32_e32 v67, v72, v72
	v_mul_f32_e32 v72, v68, v68
	v_max_f32_e32 v68, v73, v73
	v_max_f32_e32 v66, 0, v66
	v_max_f32_e32 v67, 0, v67
	v_max_f32_e32 v68, 0, v68
	v_max_f32_e32 v70, 0, v70
	v_mul_f32_e32 v66, v66, v147
	v_mul_f32_e32 v67, v67, v147
	v_mul_f32_e32 v68, v68, v147
	v_max_f32_e32 v69, 0, v69
	v_max_f32_e32 v58, v58, v58
	v_mul_f32_e32 v70, v70, v147
	v_mul_f32_e32 v66, v66, v66
	v_mul_f32_e32 v67, v67, v67
	v_mul_f32_e32 v69, v69, v147
	v_mul_f32_e32 v68, v68, v68
	v_max_f32_e32 v58, 0, v58
	v_max_f32_e32 v59, v59, v59
	v_max_f32_e32 v60, v60, v60
	v_mul_f32_e32 v70, v70, v70
	v_mul_f32_e32 v69, v69, v69
	v_cvt_pk_bf16_f32 v66, v70, v66
	v_cvt_pk_bf16_f32 v67, v67, v68
	v_cvt_pk_bf16_f32 v68, v74, v71
	v_mul_f32_e32 v58, v58, v144
	v_max_f32_e32 v59, 0, v59
	v_max_f32_e32 v60, 0, v60
	v_cvt_pk_bf16_f32 v69, v72, v69
	global_store_dwordx4 v[82:83], v[66:69], off offset:256
	v_max_f32_e32 v62, v62, v62
	v_mul_f32_e32 v59, v59, v144
	v_mul_f32_e32 v68, v58, v58
	v_max_f32_e32 v58, v63, v63
	v_mul_f32_e32 v60, v60, v144
	v_max_f32_e32 v62, 0, v62
	v_max_f32_e32 v58, 0, v58
	v_mul_f32_e32 v63, v59, v59
	v_max_f32_e32 v59, v64, v64
	v_mul_f32_e32 v64, v60, v60
	v_max_f32_e32 v60, v65, v65
	v_mul_f32_e32 v62, v62, v144
	v_mul_f32_e32 v58, v58, v144
	v_max_f32_e32 v59, 0, v59
	v_max_f32_e32 v60, 0, v60
	v_max_f32_e32 v61, v61, v61
	v_mul_f32_e32 v62, v62, v62
	v_mul_f32_e32 v58, v58, v58
	v_mul_f32_e32 v59, v59, v144
	v_mul_f32_e32 v60, v60, v144
	v_max_f32_e32 v61, 0, v61
	s_mov_b32 s13, 0x200000
	v_max_f32_e32 v50, v50, v50
	v_max_f32_e32 v51, v51, v51
; __device__ __forceinline__ unsigned cvt_pk_bf16(float lo, float hi) { unsigned r; asm volatile("v_cvt_pk_bf16_f32 %0, %1, %2" : "=v"(r) : "v"(lo), "v"(hi)); return r; }
;     __device__ __forceinline__ void operator()(const AccT& acc, const Unit& u, int wr, int wc, int fr, int fq) const {
;     ...
;         for (int ai = 0; ai < 2; ++ai)
; #pragma unroll
;             for (int m = 0; m < 4; ++m) { bf16_t* rowp = U + (size_t)(row0 + ai * 128 + m * 16) * FF + col0;
;                 const float rstd = rs[ai * 4 + m];
; #pragma unroll
;                 for (int bj = 0; bj < 2; ++bj) { f32x4 v0 = acc[ai][bj][m][0], v1 = acc[ai][bj][m][1];
; #pragma unroll
;                     for (int j = 0; j < 4; ++j) { const float a = fmaxf(v0[j], 0.f) * rstd, b = fmaxf(v1[j], 0.f) * rstd; v0[j] = a * a; v1[j] = b * b; }
;                     u32x4 w; w.x = cvt_pk_bf16(v0[0], v0[1]); w.y = cvt_pk_bf16(v0[2], v0[3]); w.z = cvt_pk_bf16(v1[0], v1[1]); w.w = cvt_pk_bf16(v1[2], v1[3]);
;                     *(u32x4*)(rowp + bj * 128) = w; } }
	v_max_f32_e32 v52, v52, v52
	v_mul_f32_e32 v59, v59, v59
	v_mul_f32_e32 v61, v61, v144
	v_mul_f32_e32 v60, v60, v60
	v_cvt_pk_bf16_f32 v58, v62, v58
	v_add_co_u32_e32 v62, vcc, s13, v142
	v_max_f32_e32 v50, 0, v50
	v_max_f32_e32 v51, 0, v51
	v_max_f32_e32 v52, 0, v52
	v_mul_f32_e32 v61, v61, v61
	v_cvt_pk_bf16_f32 v59, v59, v60
	v_cvt_pk_bf16_f32 v60, v68, v63
	v_addc_co_u32_e32 v63, vcc, 0, v143, vcc
	v_mul_f32_e32 v50, v50, v144
	v_mul_f32_e32 v51, v51, v144
	v_mul_f32_e32 v52, v52, v144
	v_cvt_pk_bf16_f32 v61, v64, v61
	global_store_dwordx4 v[62:63], v[58:61], off
	v_max_f32_e32 v54, v54, v54
	v_max_f32_e32 v53, v53, v53
	v_mul_f32_e32 v58, v50, v50
	v_max_f32_e32 v50, v55, v55
	v_mul_f32_e32 v55, v51, v51
	v_max_f32_e32 v51, v56, v56
	v_mul_f32_e32 v56, v52, v52
	v_max_f32_e32 v52, v57, v57
	v_max_f32_e32 v50, 0, v50
	v_max_f32_e32 v51, 0, v51
	v_max_f32_e32 v52, 0, v52
	v_max_f32_e32 v54, 0, v54
	v_mul_f32_e32 v50, v50, v144
	v_mul_f32_e32 v51, v51, v144
	v_mul_f32_e32 v52, v52, v144
	v_max_f32_e32 v53, 0, v53
	v_max_f32_e32 v42, v42, v42
	s_mov_b64 s[20:21], 0x200000
	v_mul_f32_e32 v54, v54, v144
	v_mul_f32_e32 v50, v50, v50
	v_mul_f32_e32 v51, v51, v51
	v_mul_f32_e32 v53, v53, v144
	v_mul_f32_e32 v52, v52, v52
	v_max_f32_e32 v42, 0, v42
	v_max_f32_e32 v43, v43, v43
	v_max_f32_e32 v44, v44, v44
	v_lshl_add_u64 v[66:67], v[142:143], 0, s[20:21]
	v_mul_f32_e32 v54, v54, v54
	v_mul_f32_e32 v53, v53, v53
	v_cvt_pk_bf16_f32 v50, v54, v50
	v_cvt_pk_bf16_f32 v51, v51, v52
	v_cvt_pk_bf16_f32 v52, v58, v55
	v_mul_f32_e32 v42, v42, v145
	v_max_f32_e32 v43, 0, v43
	v_max_f32_e32 v44, 0, v44
	v_cvt_pk_bf16_f32 v53, v56, v53
	global_store_dwordx4 v[66:67], v[50:53], off offset:256
	v_max_f32_e32 v46, v46, v46
	v_mul_f32_e32 v43, v43, v145
	v_mul_f32_e32 v52, v42, v42
	v_max_f32_e32 v42, v47, v47
	v_mul_f32_e32 v44, v44, v145
	v_max_f32_e32 v46, 0, v46
	v_max_f32_e32 v42, 0, v42
	v_mul_f32_e32 v47, v43, v43
	v_max_f32_e32 v43, v48, v48
	v_mul_f32_e32 v48, v44, v44
	v_max_f32_e32 v44, v49, v49
	v_mul_f32_e32 v46, v46, v145
	v_mul_f32_e32 v42, v42, v145
	v_max_f32_e32 v43, 0, v43
	v_max_f32_e32 v44, 0, v44
	v_max_f32_e32 v45, v45, v45
	v_mul_f32_e32 v46, v46, v46
	v_mul_f32_e32 v42, v42, v42
	v_mul_f32_e32 v43, v43, v145
	v_mul_f32_e32 v44, v44, v145
	v_max_f32_e32 v45, 0, v45
	s_mov_b32 s13, 0x240000
	v_max_f32_e32 v34, v34, v34
	v_max_f32_e32 v35, v35, v35
	v_max_f32_e32 v36, v36, v36
	v_mul_f32_e32 v43, v43, v43
	v_mul_f32_e32 v45, v45, v145
	v_mul_f32_e32 v44, v44, v44
	v_cvt_pk_bf16_f32 v42, v46, v42
	v_add_co_u32_e32 v46, vcc, s13, v142
	v_max_f32_e32 v34, 0, v34
	v_max_f32_e32 v35, 0, v35
	v_max_f32_e32 v36, 0, v36
	v_mul_f32_e32 v45, v45, v45
	v_cvt_pk_bf16_f32 v43, v43, v44
	v_cvt_pk_bf16_f32 v44, v52, v47
	v_addc_co_u32_e32 v47, vcc, 0, v143, vcc
	v_mul_f32_e32 v34, v34, v145
	v_mul_f32_e32 v35, v35, v145
	v_mul_f32_e32 v36, v36, v145
	v_cvt_pk_bf16_f32 v45, v48, v45
	global_store_dwordx4 v[46:47], v[42:45], off
	v_max_f32_e32 v38, v38, v38
	v_max_f32_e32 v37, v37, v37
	v_mul_f32_e32 v42, v34, v34
	v_max_f32_e32 v34, v39, v39
	v_mul_f32_e32 v39, v35, v35
	v_max_f32_e32 v35, v40, v40
	v_mul_f32_e32 v40, v36, v36
	v_max_f32_e32 v36, v41, v41
	v_max_f32_e32 v34, 0, v34
	v_max_f32_e32 v35, 0, v35
	v_max_f32_e32 v36, 0, v36
	v_max_f32_e32 v38, 0, v38
	v_mul_f32_e32 v34, v34, v145
	v_mul_f32_e32 v35, v35, v145
	v_mul_f32_e32 v36, v36, v145
	v_max_f32_e32 v37, 0, v37
	v_max_f32_e32 v26, v26, v26
	s_mov_b64 s[20:21], 0x240000
	v_mul_f32_e32 v38, v38, v145
	v_mul_f32_e32 v34, v34, v34
	v_mul_f32_e32 v35, v35, v35
	v_mul_f32_e32 v37, v37, v145
	v_mul_f32_e32 v36, v36, v36
	v_max_f32_e32 v26, 0, v26
	v_max_f32_e32 v27, v27, v27
	v_max_f32_e32 v28, v28, v28
	v_lshl_add_u64 v[50:51], v[142:143], 0, s[20:21]
	v_mul_f32_e32 v38, v38, v38
	v_mul_f32_e32 v37, v37, v37
	v_cvt_pk_bf16_f32 v34, v38, v34
	v_cvt_pk_bf16_f32 v35, v35, v36
	v_cvt_pk_bf16_f32 v36, v42, v39
	v_mul_f32_e32 v26, v26, v140
	v_max_f32_e32 v27, 0, v27
	v_max_f32_e32 v28, 0, v28
	v_cvt_pk_bf16_f32 v37, v40, v37
	global_store_dwordx4 v[50:51], v[34:37], off offset:256
	v_max_f32_e32 v30, v30, v30
	v_mul_f32_e32 v27, v27, v140
	v_mul_f32_e32 v36, v26, v26
	v_max_f32_e32 v26, v31, v31
	v_mul_f32_e32 v28, v28, v140
	v_max_f32_e32 v30, 0, v30
	v_max_f32_e32 v26, 0, v26
	v_mul_f32_e32 v31, v27, v27
	v_max_f32_e32 v27, v32, v32
	v_mul_f32_e32 v32, v28, v28
; __device__ __forceinline__ unsigned cvt_pk_bf16(float lo, float hi) { unsigned r; asm volatile("v_cvt_pk_bf16_f32 %0, %1, %2" : "=v"(r) : "v"(lo), "v"(hi)); return r; }
; #define PG8_BAR __builtin_amdgcn_s_barrier()
;     ...
;         if (!has_next) break;
; #pragma unroll
;         for (int a = 0; a < 2; ++a)
; #pragma unroll
;             for (int b = 0; b < 2; ++b)
; #pragma unroll
;                 for (int m = 0; m < 4; ++m)
; #pragma unroll
;                     for (int n = 0; n < 2; ++n) acc[a][b][m][n] = (f32x4){0.f, 0.f, 0.f, 0.f};
;         cur = nxt; cA = nA; cB = nB; ++ui;
;         if (wr == 1) PG8_BAR;
;     __device__ __forceinline__ void operator()(const AccT& acc, const Unit& u, int wr, int wc, int fr, int fq) const {
;     ...
;         for (int ai = 0; ai < 2; ++ai)
; #pragma unroll
;             for (int m = 0; m < 4; ++m) { bf16_t* rowp = U + (size_t)(row0 + ai * 128 + m * 16) * FF + col0;
;                 const float rstd = rs[ai * 4 + m];
; #pragma unroll
;                 for (int bj = 0; bj < 2; ++bj) { f32x4 v0 = acc[ai][bj][m][0], v1 = acc[ai][bj][m][1];
; #pragma unroll
;                     for (int j = 0; j < 4; ++j) { const float a = fmaxf(v0[j], 0.f) * rstd, b = fmaxf(v1[j], 0.f) * rstd; v0[j] = a * a; v1[j] = b * b; }
;                     u32x4 w; w.x = cvt_pk_bf16(v0[0], v0[1]); w.y = cvt_pk_bf16(v0[2], v0[3]); w.z = cvt_pk_bf16(v1[0], v1[1]); w.w = cvt_pk_bf16(v1[2], v1[3]);
;                     *(u32x4*)(rowp + bj * 128) = w; } }
	v_max_f32_e32 v28, v33, v33
	v_mul_f32_e32 v30, v30, v140
	v_mul_f32_e32 v26, v26, v140
	v_max_f32_e32 v27, 0, v27
	v_max_f32_e32 v28, 0, v28
	v_max_f32_e32 v29, v29, v29
	v_mul_f32_e32 v30, v30, v30
	v_mul_f32_e32 v26, v26, v26
	v_mul_f32_e32 v27, v27, v140
	v_mul_f32_e32 v28, v28, v140
	v_max_f32_e32 v29, 0, v29
	s_mov_b32 s13, 0x280000
	v_max_f32_e32 v18, v18, v18
	v_max_f32_e32 v19, v19, v19
	v_max_f32_e32 v20, v20, v20
	v_mul_f32_e32 v27, v27, v27
	v_mul_f32_e32 v29, v29, v140
	v_mul_f32_e32 v28, v28, v28
	v_cvt_pk_bf16_f32 v26, v30, v26
	v_add_co_u32_e32 v30, vcc, s13, v142
	v_max_f32_e32 v18, 0, v18
	v_max_f32_e32 v19, 0, v19
	v_max_f32_e32 v20, 0, v20
	v_mul_f32_e32 v29, v29, v29
	v_cvt_pk_bf16_f32 v27, v27, v28
	v_cvt_pk_bf16_f32 v28, v36, v31
	v_addc_co_u32_e32 v31, vcc, 0, v143, vcc
	v_mul_f32_e32 v18, v18, v140
	v_mul_f32_e32 v19, v19, v140
	v_mul_f32_e32 v20, v20, v140
	v_cvt_pk_bf16_f32 v29, v32, v29
	global_store_dwordx4 v[30:31], v[26:29], off
	v_max_f32_e32 v22, v22, v22
	v_max_f32_e32 v21, v21, v21
	v_mul_f32_e32 v26, v18, v18
	v_max_f32_e32 v18, v23, v23
	v_mul_f32_e32 v23, v19, v19
	v_max_f32_e32 v19, v24, v24
	v_mul_f32_e32 v24, v20, v20
	v_max_f32_e32 v20, v25, v25
	v_max_f32_e32 v18, 0, v18
	v_max_f32_e32 v19, 0, v19
	v_max_f32_e32 v20, 0, v20
	v_max_f32_e32 v22, 0, v22
	v_mul_f32_e32 v18, v18, v140
	v_mul_f32_e32 v19, v19, v140
	v_mul_f32_e32 v20, v20, v140
	v_max_f32_e32 v21, 0, v21
	v_max_f32_e32 v10, v10, v10
	s_mov_b64 s[20:21], 0x280000
	v_mul_f32_e32 v22, v22, v140
	v_mul_f32_e32 v18, v18, v18
	v_mul_f32_e32 v19, v19, v19
	v_mul_f32_e32 v21, v21, v140
	v_mul_f32_e32 v20, v20, v20
	v_max_f32_e32 v10, 0, v10
	v_max_f32_e32 v11, v11, v11
	v_max_f32_e32 v12, v12, v12
	v_lshl_add_u64 v[34:35], v[142:143], 0, s[20:21]
	v_mul_f32_e32 v22, v22, v22
	v_mul_f32_e32 v21, v21, v21
	v_cvt_pk_bf16_f32 v18, v22, v18
	v_cvt_pk_bf16_f32 v19, v19, v20
	v_cvt_pk_bf16_f32 v20, v26, v23
	v_mul_f32_e32 v10, v10, v141
	v_max_f32_e32 v11, 0, v11
	v_max_f32_e32 v12, 0, v12
	v_cvt_pk_bf16_f32 v21, v24, v21
	global_store_dwordx4 v[34:35], v[18:21], off offset:256
	v_max_f32_e32 v14, v14, v14
	v_mul_f32_e32 v11, v11, v141
	v_mul_f32_e32 v20, v10, v10
	v_max_f32_e32 v10, v15, v15
	v_mul_f32_e32 v12, v12, v141
	v_max_f32_e32 v14, 0, v14
	v_max_f32_e32 v10, 0, v10
	v_mul_f32_e32 v15, v11, v11
	v_max_f32_e32 v11, v16, v16
	v_mul_f32_e32 v16, v12, v12
	v_max_f32_e32 v12, v17, v17
	v_mul_f32_e32 v14, v14, v141
	v_mul_f32_e32 v10, v10, v141
	v_max_f32_e32 v11, 0, v11
	v_max_f32_e32 v12, 0, v12
	v_max_f32_e32 v13, v13, v13
	v_mul_f32_e32 v14, v14, v14
	v_mul_f32_e32 v10, v10, v10
	v_mul_f32_e32 v11, v11, v141
	v_mul_f32_e32 v12, v12, v141
	v_max_f32_e32 v13, 0, v13
	s_mov_b32 s13, 0x2c0000
	v_max_f32_e32 v2, v2, v2
	v_max_f32_e32 v3, v3, v3
	v_max_f32_e32 v4, v4, v4
	v_mul_f32_e32 v11, v11, v11
	v_mul_f32_e32 v13, v13, v141
	v_mul_f32_e32 v12, v12, v12
	v_cvt_pk_bf16_f32 v10, v14, v10
	v_add_co_u32_e32 v14, vcc, s13, v142
	v_max_f32_e32 v2, 0, v2
	v_max_f32_e32 v3, 0, v3
	v_max_f32_e32 v4, 0, v4
	v_mul_f32_e32 v13, v13, v13
	v_cvt_pk_bf16_f32 v11, v11, v12
	v_cvt_pk_bf16_f32 v12, v20, v15
	v_addc_co_u32_e32 v15, vcc, 0, v143, vcc
	v_mul_f32_e32 v2, v2, v141
	v_mul_f32_e32 v3, v3, v141
	v_mul_f32_e32 v4, v4, v141
	v_cvt_pk_bf16_f32 v13, v16, v13
	global_store_dwordx4 v[14:15], v[10:13], off
	v_max_f32_e32 v5, v5, v5
	v_max_f32_e32 v6, v6, v6
	v_mul_f32_e32 v10, v2, v2
	v_max_f32_e32 v2, v7, v7
	v_mul_f32_e32 v7, v3, v3
	v_max_f32_e32 v3, v8, v8
	v_mul_f32_e32 v8, v4, v4
	v_max_f32_e32 v4, v9, v9
	v_max_f32_e32 v2, 0, v2
	v_max_f32_e32 v3, 0, v3
	v_max_f32_e32 v4, 0, v4
	v_max_f32_e32 v5, 0, v5
	s_mov_b64 s[20:21], 0x2c0000
	v_max_f32_e32 v6, 0, v6
	v_mul_f32_e32 v2, v2, v141
	v_mul_f32_e32 v3, v3, v141
	v_mul_f32_e32 v4, v4, v141
	v_mul_f32_e32 v5, v5, v141
	v_lshl_add_u64 v[18:19], v[142:143], 0, s[20:21]
	v_mul_f32_e32 v6, v6, v141
	v_mul_f32_e32 v2, v2, v2
	v_mul_f32_e32 v3, v3, v3
	v_mul_f32_e32 v4, v4, v4
	v_mul_f32_e32 v5, v5, v5
	s_andn2_b64 vcc, exec, s[44:45]
	s_mov_b64 s[20:21], -1
	v_mul_f32_e32 v6, v6, v6
	v_cvt_pk_bf16_f32 v2, v6, v2
	v_cvt_pk_bf16_f32 v3, v3, v4
	v_cvt_pk_bf16_f32 v4, v10, v7
	v_cvt_pk_bf16_f32 v5, v8, v5
	global_store_dwordx4 v[18:19], v[2:5], off offset:256
	s_cbranch_vccnz .LBB0_766
	s_andn2_b64 vcc, exec, s[6:7]
	s_cbranch_vccnz .LBB0_765
	s_branch .LBB0_765
